# rwc producers: y-partial records (64 B apart) read with a per-lane XOR chunk order (k ^ ((lane>>2)&3)) so the four ds_read_b128 are bank-conflict free; same pair sums, bit-identical
# speedup vs baseline: 1.0200x; 1.0175x over previous
; __device__ __forceinline__ int ltid(int wvs) { int t = (wvs << 6) | (int)__builtin_amdgcn_mbcnt_hi(~0u, __builtin_amdgcn_mbcnt_lo(~0u, 0u)); asm volatile("" : "+v"(t)); return t; }
; __device__ __forceinline__ int lbid() { int b = __builtin_amdgcn_workgroup_id_x(); asm volatile("" : "+s"(b)); return b; }
; __device__ __forceinline__ void phase_rwc(const int wvs, const Params& p, LAS unsigned char* lds, int layer, int wg0) {
;   const int wgi = lbid() - wg0; if (wgi < 0 || wgi >= NB * 48) return;
;   const int tid = ltid(wvs), wv = tid >> 6, lane = tid & 63;
;   const int qd = wgi / 48, chain = wgi - qd * 48, d = chain & 1, h = (chain >> 1) % 6, b = chain / 12; const int v0 = qd * 16;
;   constexpr int BUFSZ = 5 * 8192 + 2048, NBLK = TPB / 32, YOFF = 2 * BUFSZ, YSZ = 32 * 16 * 16 * 4;
;   hf* P = (hf*)(p.ws + OFF_BIG); const hf* RL = (const hf*)(p.ws + OFF_RL1); const float* INVN = (const float*)(p.ws + OFF_INVN);
;   const size_t tb = (size_t)b * TPB;
;     ...
;   if (wv >= 4) {
;     const int pt = tid - 256;
;     h4 nr[2], nk[2], ne[2], na[2]; float ninv[2]; h2 nv;
;     f32x4 kkw[2], kaw[2];
; #pragma unroll
;     for (int j = 0; j < 2; ++j) { const int kg = (pt + 256 * j) & 15; kkw[j] = *(const f32x4*)(p.in[I_KK] + layer * 384 + h * 64 + kg * 4); kaw[j] = *(const f32x4*)(p.in[I_KA] + layer * 384 + h * 64 + kg * 4); }
;     hf* ybase; long ypitch;
;     if (d == 0) { ybase = (hf*)(p.ws + OFF_GV) + h * 64 + v0; ypitch = 384; }
;     else if (h < 4) { ybase = P + PC_RL2 + h * 64 + v0; ypitch = PP; }
;     else { ybase = (hf*)(p.ws + OFF_YB2) + (h - 4) * 64 + v0; ypitch = 128; }
.LBB0_1248:
	s_andn2_saveexec_b64 s[8:9], s[6:7]
	s_cbranch_execz .LBB0_1366
	v_and_b32_e32 v94, 12, v193
	v_lshlrev_b32_e32 v94, 2, v94
	s_sub_i32 s2, s10, 48
	s_load_dwordx4 s[20:23], s[4:5], 0xf8
	s_load_dwordx2 s[16:17], s[4:5], 0x138
	s_mul_i32 s4, s2, 0xab
	s_bfe_u32 s48, s4, 0x3000d
	s_mul_i32 s4, s48, 0xffffffd0
	s_add_i32 s2, s4, s2
	s_lshr_b32 s4, s2, 1
	s_bfe_i32 s5, s4, 0x80000
	s_mul_i32 s5, s5, 43
	s_bfe_u32 s6, s5, 0x1000f
	s_bfe_u32 s5, s5, 0x80008
	s_add_i32 s5, s5, s6
	s_mul_i32 s5, s5, 6
	s_sub_i32 s4, s4, s5
	s_and_b32 s15, s10, 1
	s_bfe_i32 s10, s4, 0x80000
	s_sext_i32_i8 s4, s4
	s_waitcnt lgkmcnt(0)
	s_add_u32 s6, s20, s90
	s_addc_u32 s7, s21, s91
	s_lshl_b32 s12, s4, 6
	s_ashr_i32 s13, s12, 31
	s_lshl_b64 s[4:5], s[12:13], 2
	v_lshlrev_b32_e32 v0, 2, v25
	s_add_u32 s6, s6, s4
	v_and_b32_e32 v0, 60, v0
	s_addc_u32 s7, s7, s5
	v_lshlrev_b32_e32 v38, 2, v0
	global_load_dwordx4 v[2:5], v38, s[6:7]
	s_add_u32 s6, s22, s90
	s_addc_u32 s7, s23, s91
	s_add_u32 s4, s6, s4
	s_addc_u32 s5, s7, s5
	global_load_dwordx4 v[6:9], v38, s[4:5]
	s_cmp_eq_u32 s15, 0
	s_cselect_b64 s[4:5], -1, 0
	s_cmp_eq_u32 s15, 1
	s_cselect_b64 s[22:23], -1, 0
	s_mov_b64 s[6:7], -1
	s_and_b64 vcc, exec, s[22:23]
	s_sext_i32_i16 s14, s10
	s_cbranch_vccz .LBB0_1255
	s_cmp_gt_i32 s14, 3
	s_cbranch_scc0 .LBB0_1252
	s_lshl_b64 s[6:7], s[12:13], 1
	s_add_u32 s6, s16, s6
	s_addc_u32 s7, s17, s7
	s_add_u32 s20, s6, 0xfbb1e00
	s_addc_u32 s21, s7, 0
	s_mov_b64 s[6:7], 0

.LBB0_1320:
	s_cmp_eq_u32 s24, 0
	v_add_u32_e32 v66, 0, v58
	s_cbranch_scc1 .LBB0_1330
	v_add_u32_e32 v14, 0x1d000, v66
	v_xor_b32_e32 v95, v94, v14
	v_xor_b32_e32 v96, 16, v95
	v_xor_b32_e32 v97, 32, v95
	v_xor_b32_e32 v98, 48, v95
	ds_read_b128 v[18:21], v95
	ds_read_b128 v[22:25], v96
	ds_read_b128 v[10:13], v97
	ds_read_b128 v[14:17], v98
	s_lshl_b32 s2, s25, 5
	s_sub_i32 s2, s2, 32
	s_and_b64 vcc, exec, s[6:7]
	v_add_u32_e32 v50, s2, v52
	s_cbranch_vccnz .LBB0_1325
	v_add_u32_e32 v51, s24, v52
	v_subrev_u32_e32 v51, 32, v51
	v_cmp_gt_u32_e32 vcc, s33, v51
	v_mov_b32_e32 v51, v62
	s_and_saveexec_b64 s[22:23], vcc
	v_sub_u32_e32 v51, 0xff, v50
	s_or_b64 exec, exec, s[22:23]
	v_mov_b32_e32 v50, v51
.LBB0_1325:
	s_waitcnt lgkmcnt(2)
	v_pk_add_f32 v[20:21], v[20:21], v[24:25]
	v_pk_add_f32 v[18:19], v[18:19], v[22:23]
	s_waitcnt lgkmcnt(0)
	v_pk_add_f32 v[12:13], v[12:13], v[16:17]
	v_pk_add_f32 v[10:11], v[10:11], v[14:15]
	v_pk_add_f32 v[12:13], v[20:21], v[12:13]
	v_pk_add_f32 v[10:11], v[18:19], v[10:11]
	v_ashrrev_i32_e32 v51, 31, v50
	v_add_f32_e32 v10, v10, v11
	v_add_f32_e32 v11, v12, v13
	v_add_f32_e32 v10, v10, v11
	v_cvt_f16_f32_e32 v12, v10
	v_lshl_add_u64 v[10:11], s[16:17], 0, v[50:51]
	v_mul_lo_u32 v13, v11, s10
	v_mul_lo_u32 v14, v10, s11
	v_mad_u64_u32 v[10:11], s[22:23], v10, s10, 0
	v_add3_u32 v11, v11, v14, v13
	v_lshl_add_u64 v[10:11], v[10:11], 1, v[26:27]
	global_store_short v[10:11], v12, off
	v_add_u32_e32 v10, 0, v57
	v_add_u32_e32 v14, 0x1d000, v10
	v_xor_b32_e32 v95, v94, v14
	v_xor_b32_e32 v96, 16, v95
	v_xor_b32_e32 v97, 32, v95
	v_xor_b32_e32 v98, 48, v95
	ds_read_b128 v[18:21], v95
	ds_read_b128 v[22:25], v96
	ds_read_b128 v[10:13], v97
	ds_read_b128 v[14:17], v98
	v_add_u32_e32 v50, s2, v53
	s_and_b64 vcc, exec, s[6:7]
	s_cbranch_vccnz .LBB0_1329
	v_add_u32_e32 v51, s24, v53
	v_subrev_u32_e32 v51, 32, v51
	v_cmp_gt_u32_e32 vcc, s33, v51
	v_mov_b32_e32 v51, v63
	s_and_saveexec_b64 s[22:23], vcc
	v_sub_u32_e32 v51, 0xff, v50
	s_or_b64 exec, exec, s[22:23]
	v_mov_b32_e32 v50, v51

.LBB0_1354:
	v_add_u32_e32 v14, 0x15000, v66
	v_xor_b32_e32 v95, v94, v14
	v_xor_b32_e32 v96, 16, v95
	v_xor_b32_e32 v97, 32, v95
	v_xor_b32_e32 v98, 48, v95
	ds_read_b128 v[18:21], v95
	ds_read_b128 v[22:25], v96
	ds_read_b128 v[10:13], v97
	ds_read_b128 v[14:17], v98
	s_and_b64 vcc, exec, s[6:7]
	s_cbranch_vccnz .LBB0_1360
	v_add_u32_e32 v51, s22, v52
	v_cmp_lt_u32_e32 vcc, s29, v50
	s_and_saveexec_b64 s[20:21], vcc
	s_xor_b64 s[20:21], exec, s[20:21]
	v_sub_u32_e32 v50, 0x11ff, v51
	s_andn2_saveexec_b64 s[20:21], s[20:21]
	v_sub_u32_e32 v50, 0xff, v51
	s_or_b64 exec, exec, s[20:21]
.LBB0_1360:
	s_waitcnt lgkmcnt(2)
	v_pk_add_f32 v[20:21], v[20:21], v[24:25]
	v_pk_add_f32 v[18:19], v[18:19], v[22:23]
	s_waitcnt lgkmcnt(0)
	v_pk_add_f32 v[12:13], v[12:13], v[16:17]
	v_pk_add_f32 v[10:11], v[10:11], v[14:15]
	v_pk_add_f32 v[12:13], v[20:21], v[12:13]
	v_pk_add_f32 v[10:11], v[18:19], v[10:11]
	v_ashrrev_i32_e32 v51, 31, v50
	v_add_f32_e32 v10, v10, v11
	v_add_f32_e32 v11, v12, v13
	v_add_f32_e32 v10, v10, v11
	v_cvt_f16_f32_e32 v12, v10
	v_lshl_add_u64 v[10:11], s[16:17], 0, v[50:51]
	v_mul_lo_u32 v13, v11, s10
	v_mul_lo_u32 v14, v10, s11
	v_mad_u64_u32 v[10:11], s[20:21], v10, s10, 0
	v_add3_u32 v11, v11, v14, v13
	v_lshl_add_u64 v[10:11], v[10:11], 1, v[26:27]
	global_store_short v[10:11], v12, off
	v_add_u32_e32 v10, 0, v57
	v_add_u32_e32 v14, 0x15000, v10
	v_xor_b32_e32 v95, v94, v14
	v_xor_b32_e32 v96, 16, v95
	v_xor_b32_e32 v97, 32, v95
	v_xor_b32_e32 v98, 48, v95
	ds_read_b128 v[18:21], v95
	ds_read_b128 v[22:25], v96
	ds_read_b128 v[10:13], v97
	ds_read_b128 v[14:17], v98
	v_add_u32_e32 v50, s24, v53
	s_and_b64 vcc, exec, s[6:7]
	s_cbranch_vccnz .LBB0_1301
	v_add_u32_e32 v51, s22, v53
	v_cmp_lt_u32_e32 vcc, s29, v50
	s_and_saveexec_b64 s[20:21], vcc
	s_xor_b64 s[20:21], exec, s[20:21]
	v_sub_u32_e32 v50, 0x11ff, v51
	s_andn2_saveexec_b64 s[20:21], s[20:21]
	s_cbranch_execz .LBB0_1300
	v_sub_u32_e32 v50, 0xff, v51
	s_branch .LBB0_1300
.LBB0_1365:
	s_add_i32 s2, 0, 0x1d000
	v_add_u32_e32 v0, s2, v58
	v_xor_b32_e32 v95, v94, v0
	v_xor_b32_e32 v96, 16, v95
	v_xor_b32_e32 v97, 32, v95
	v_xor_b32_e32 v98, 48, v95
	ds_read_b128 v[2:5], v95
	ds_read_b128 v[6:9], v96
	ds_read_b128 v[10:13], v97
	ds_read_b128 v[14:17], v98
	s_waitcnt lgkmcnt(2)
	v_pk_add_f32 v[4:5], v[4:5], v[8:9]
	v_pk_add_f32 v[2:3], v[2:3], v[6:7]
	s_waitcnt lgkmcnt(0)
	v_pk_add_f32 v[6:7], v[12:13], v[16:17]
	v_pk_add_f32 v[8:9], v[10:11], v[14:15]
	v_pk_add_f32 v[4:5], v[4:5], v[6:7]
	v_pk_add_f32 v[2:3], v[2:3], v[8:9]
	s_nop 0
	v_add_f32_e32 v0, v2, v3
	v_add_f32_e32 v2, v4, v5
	v_add_f32_e32 v0, v0, v2
	v_add_u32_e32 v2, 0x10e0, v52
	v_sub_u32_e32 v3, 0x11f, v52
	v_cndmask_b32_e64 v2, v3, v2, s[4:5]
	v_ashrrev_i32_e32 v3, 31, v2
	v_cvt_f16_f32_e32 v0, v0
	v_lshl_add_u64 v[2:3], s[16:17], 0, v[2:3]
	v_mul_lo_u32 v4, s11, v2
	v_mul_lo_u32 v5, s10, v3
	v_mad_u64_u32 v[2:3], s[6:7], s10, v2, 0
	v_add3_u32 v3, v3, v5, v4
	v_lshl_add_u64 v[2:3], v[2:3], 1, v[26:27]
	global_store_short v[2:3], v0, off
	v_add_u32_e32 v0, s2, v57
	v_xor_b32_e32 v95, v94, v0
	v_xor_b32_e32 v96, 16, v95
	v_xor_b32_e32 v97, 32, v95
	v_xor_b32_e32 v98, 48, v95
	ds_read_b128 v[2:5], v95
	ds_read_b128 v[6:9], v96
	ds_read_b128 v[10:13], v97
	ds_read_b128 v[14:17], v98
	s_waitcnt lgkmcnt(2)
	v_pk_add_f32 v[4:5], v[4:5], v[8:9]
	v_pk_add_f32 v[2:3], v[2:3], v[6:7]
	s_waitcnt lgkmcnt(0)
	v_pk_add_f32 v[6:7], v[12:13], v[16:17]
	v_pk_add_f32 v[8:9], v[10:11], v[14:15]
	v_pk_add_f32 v[4:5], v[4:5], v[6:7]
	v_pk_add_f32 v[2:3], v[2:3], v[8:9]
	s_nop 0
	v_add_f32_e32 v0, v2, v3
	v_add_f32_e32 v2, v4, v5
	v_add_f32_e32 v0, v0, v2
	v_add_u32_e32 v2, 0x10e0, v53
	v_sub_u32_e32 v3, 0x11f, v53
	v_cndmask_b32_e64 v2, v3, v2, s[4:5]
	v_ashrrev_i32_e32 v3, 31, v2
	v_cvt_f16_f32_e32 v0, v0
	v_lshl_add_u64 v[2:3], s[16:17], 0, v[2:3]
	v_mul_lo_u32 v4, s11, v2
	v_mul_lo_u32 v5, s10, v3
	v_mad_u64_u32 v[2:3], s[4:5], s10, v2, 0
	v_add3_u32 v3, v3, v5, v4
	v_lshl_add_u64 v[2:3], v[2:3], 1, v[26:27]
	global_store_short v[2:3], v0, off
